# attention QK: MFMA order swapped in odd segments so same-accumulator MFMAs are adjacent in matrix-pipe order
# speedup vs baseline: 1.0023x; 1.0023x over previous
; template <int MODE, int VARI>
; __device__ __forceinline__ void attn_unit(LAS unsigned char* lds, const int tid, const AttnP& a, float c2, float lam, const float* subln, float outscale, float fox_u, const bool fast) {
;     ...
;       unsigned voff[2], koff[KW / 64], kstp[KW / 64], boff = 0; int vt = t_lo, kt = t_lo;
;       { int tt_ = tid; asm volatile("" : "+v"(tt_)); const int ln_ = tt_ & 63;
; #pragma unroll
;         for (int i_ = 0; i_ < 2; ++i_) { const int ch_ = wid + 8 * i_, b_ = ch_ * 1024 + ln_ * 16, sub_ = b_ >> 9, wi_ = (b_ & 511) >> 1;
;             const int kk_ = (sub_ >> 2) * 8 + (wi_ >> 5), c_ = (sub_ & 3) * 32 + (wi_ & 31), k_ = (kk_ & ~0xC) | ((kk_ & 4) << 1) | ((kk_ & 8) >> 1);
;             voff[i_] = (unsigned)(((t_lo * 64 + k_) * a.vpitch + c_) * 2); }
; #pragma unroll
;         for (int i_ = 0; i_ < KW / 64; ++i_) { const int ch_ = wid + 8 * i_, b_ = ch_ * 1024 + ln_ * 16, krow_ = b_ / (KW * 2), cs_ = (b_ % (KW * 2)) >> 4;
;             const int kcc_ = cs_ ^ (kswz<KW>(krow_) >> 4);
;             if (MODE == 2 && kcc_ >= 8) { koff[i_] = (unsigned)((const char*)a.K1 - (const char*)a.K0) + (unsigned)(((t_lo * 64 + krow_) * a.k1pitch + (kcc_ - 8) * 8) * 2); kstp[i_] = (unsigned)(64 * a.k1pitch * 2); }
;             else { koff[i_] = (unsigned)(((t_lo * 64 + krow_) * a.k0pitch + kcc_ * 8) * 2); kstp[i_] = (unsigned)(64 * a.k0pitch * 2); } }
;         if (MODE == 1) boff = (unsigned)((t_lo * 64 + ln_) * 32); }
.LBB0_626:
	s_lshl_b32 s2, s9, 14
	s_add_i32 s2, s58, s2
	v_lshl_add_u64 v[2:3], s[60:61], 0, v[0:1]
	v_lshl_add_u64 v[2:3], v[2:3], 0, s[96:97]
	s_mov_b32 m0, s2
	v_mov_b32_e32 v15, v1
	global_load_lds_dwordx4 v[2:3], off
	v_lshl_add_u64 v[2:3], s[60:61], 0, v[14:15]
	v_lshl_add_u64 v[2:3], v[2:3], 0, s[96:97]
	s_add_i32 m0, s2, 0x2000
	s_cmp_lt_u32 s27, s59
	global_load_lds_dwordx4 v[2:3], off
	s_cselect_b64 vcc, -1, 0
	v_add_u32_e32 v2, 0x30000, v0
	v_add_u32_e32 v3, 0x30000, v14
	s_cmp_lg_u64 vcc, 0
	v_cndmask_b32_e32 v14, v14, v3, vcc
	v_cndmask_b32_e32 v0, v0, v2, vcc
	s_addc_u32 s27, s27, 0
	s_mul_i32 s2, s12, 0x6000
	v_add_u32_e32 v15, s2, v236
	v_add_u32_e32 v6, v15, v241
	ds_read_b128 v[2:5], v6
	ds_read_b128 v[6:9], v6 offset:12288
	v_exp_f32_e32 v12, v96
	s_waitcnt lgkmcnt(0)
	v_mfma_f32_32x32x16_bf16 v[112:127], v[2:5], v[144:147], 0
	v_mov_b32_e32 v2, v97
	v_exp_f32_e32 v96, v98
	v_exp_f32_e32 v97, v99
	v_exp_f32_e32 v13, v2
	v_mfma_f32_32x32x16_bf16 v[128:143], v[6:9], v[144:147], 0
	v_add_u32_e32 v2, v15, v242
	ds_read_b128 v[4:7], v2
	ds_read_b128 v[8:11], v2 offset:12288
	v_mov_b32_e32 v2, v100
	v_mov_b32_e32 v3, v101
	v_exp_f32_e32 v98, v2
	v_exp_f32_e32 v99, v3
	v_exp_f32_e32 v100, v102
	v_exp_f32_e32 v101, v103
	v_cvt_pk_bf16_f32 v2, v12, v13
	s_waitcnt lgkmcnt(0)
	v_mfma_f32_32x32x16_bf16 v[112:127], v[4:7], v[148:151], v[112:127]
	v_cvt_pk_bf16_f32 v3, v96, v97
	v_cvt_pk_bf16_f32 v4, v98, v99
	v_cvt_pk_bf16_f32 v5, v100, v101
	s_nop 0
	v_permlane32_swap_b32_e32 v2, v4
	v_permlane32_swap_b32_e32 v3, v5
	v_mfma_f32_32x32x16_bf16 v[128:143], v[8:11], v[148:151], v[128:143]
	v_add_u32_e32 v10, v15, v243
	ds_read_b128 v[6:9], v10
	v_add_f32_e64 v102, v214, v12
	v_add_f32_e64 v103, v215, v13
	ds_read_b128 v[10:13], v10 offset:12288
	v_exp_f32_e32 v104, v104
	v_exp_f32_e32 v105, v105
	s_waitcnt lgkmcnt(0)
	v_mfma_f32_32x32x16_bf16 v[112:127], v[6:9], v[152:155], v[112:127]
	v_add_f32_e64 v6, v96, v102
	v_add_f32_e64 v7, v97, v103
	v_exp_f32_e32 v102, v106
	v_exp_f32_e32 v103, v107
	v_pk_add_f32 v[6:7], v[98:99], v[6:7]
	s_nop 0
	v_pk_add_f32 v[6:7], v[100:101], v[6:7]
	s_nop 0
	v_pk_add_f32 v[100:101], v[104:105], v[6:7]
	v_mfma_f32_32x32x16_bf16 v[128:143], v[10:13], v[152:155], v[128:143]
	v_add_u32_e32 v6, v15, v244
	ds_read_b128 v[8:11], v6
	ds_read_b128 v[96:99], v6 offset:12288
	v_exp_f32_e32 v106, v108
	v_exp_f32_e32 v107, v109
	v_exp_f32_e32 v108, v110
	v_exp_f32_e32 v109, v111
	v_cvt_pk_bf16_f32 v6, v104, v105
	s_waitcnt lgkmcnt(0)
	v_mfma_f32_32x32x16_bf16 v[112:127], v[8:11], v[156:159], v[112:127]
	v_cvt_pk_bf16_f32 v7, v102, v103
	v_cvt_pk_bf16_f32 v8, v106, v107
	v_cvt_pk_bf16_f32 v9, v108, v109
	s_nop 0
	v_permlane32_swap_b32_e32 v6, v8
	v_permlane32_swap_b32_e32 v7, v9
	v_mfma_f32_32x32x16_bf16 v[128:143], v[96:99], v[156:159], v[128:143]
	v_add_u32_e32 v96, v15, v245
	ds_read_b128 v[10:13], v96
	ds_read_b128 v[96:99], v96 offset:12288
	v_exp_f32_e32 v104, v80
	s_waitcnt lgkmcnt(0)
	v_mfma_f32_32x32x16_bf16 v[112:127], v[10:13], v[160:163], v[112:127]
	v_exp_f32_e32 v105, v81
	v_exp_f32_e32 v110, v82
	v_exp_f32_e32 v111, v83
	v_mfma_f32_32x32x16_bf16 v[128:143], v[96:99], v[160:163], v[128:143]
	v_add_u32_e32 v80, v15, v246
	ds_read_b128 v[10:13], v80
	ds_read_b128 v[80:83], v80 offset:12288
	v_exp_f32_e32 v96, v84
	v_exp_f32_e32 v97, v85
	v_exp_f32_e32 v98, v86
	v_exp_f32_e32 v99, v87
	v_cvt_pk_bf16_f32 v192, v104, v105
	v_cvt_pk_bf16_f32 v193, v110, v111
	v_cvt_pk_bf16_f32 v194, v96, v97
	v_cvt_pk_bf16_f32 v195, v98, v99
	s_waitcnt lgkmcnt(0)
	v_mfma_f32_32x32x16_bf16 v[128:143], v[80:83], v[164:167], v[128:143]
	v_permlane32_swap_b32_e32 v192, v194
	v_permlane32_swap_b32_e32 v193, v195
	v_mfma_f32_32x32x16_bf16 v[112:127], v[10:13], v[164:167], v[112:127]
	v_add_u32_e32 v80, v15, v247
	ds_read_b128 v[10:13], v80
	ds_read_b128 v[80:83], v80 offset:12288
	s_waitcnt lgkmcnt(0)
	v_mfma_f32_32x32x16_bf16 v[112:127], v[10:13], v[168:171], v[112:127]
	v_exp_f32_e32 v10, v88
	v_exp_f32_e32 v11, v89
	v_exp_f32_e32 v12, v90
	v_exp_f32_e32 v13, v91
	v_mfma_f32_32x32x16_bf16 v[128:143], v[80:83], v[168:171], v[128:143]
	v_mov_b32_e32 v88, v92
	v_mov_b32_e32 v89, v93
	v_add_f32_e64 v92, v102, v100
	v_add_f32_e64 v93, v103, v101
	v_add_u32_e32 v84, v15, v248
	v_pk_add_f32 v[92:93], v[106:107], v[92:93]
	v_pk_add_f32 v[92:93], v[108:109], v[92:93]
	v_pk_add_f32 v[92:93], v[104:105], v[92:93]
	v_exp_f32_e32 v88, v88
	v_pk_add_f32 v[92:93], v[110:111], v[92:93]
	v_exp_f32_e32 v89, v89
	v_pk_add_f32 v[92:93], v[96:97], v[92:93]
	ds_read_b128 v[80:83], v84
	ds_read_b128 v[84:87], v84 offset:12288
	v_exp_f32_e32 v90, v94
	v_exp_f32_e32 v91, v95
	v_pk_add_f32 v[92:93], v[98:99], v[92:93]
	s_waitcnt lgkmcnt(0)
; #define SBAR() __builtin_amdgcn_sched_barrier(0)
; #define VSET(S, d0) do { constexpr int b_ = (d0) * 512; TRRD(S##l0, b_); TRRD(S##h0, b_ + 2048); TRRD(S##l1, b_ + 4096); TRRD(S##h1, b_ + 6144); \
;         TRRD(S##l2, b_ + 8192); TRRD(S##h2, b_ + 10240); TRRD(S##l3, b_ + 12288); TRRD(S##h3, b_ + 14336); } while (0)
; #define LWAIT(n) do { asm volatile("s_waitcnt lgkmcnt(" #n ")" ::: "memory"); SBAR(); } while (0)
; __device__ __forceinline__ void pv_tile(f32x16* o, unsigned vb, bf16x8 pa0, bf16x8 pa1, bf16x8 pa2, bf16x8 pa3) {
;     ...
;     s16x4 Al0, Al1, Al2, Al3, Ah0, Ah1, Ah2, Ah3, Bl0, Bl1, Bl2, Bl3, Bh0, Bh1, Bh2, Bh3;
;     VSET(A, 0);
;     VSET(B, 1); LWAIT(8); VMMA(A, 0); SBAR();
;     VSET(A, 2); LWAIT(8); VMMA(B, 1); SBAR();
;     VSET(B, 3); LWAIT(8); VMMA(A, 2); SBAR();
;     LWAIT(0); VMMA(B, 3);
	v_mfma_f32_32x32x16_bf16 v[128:143], v[84:87], v[172:175], v[128:143]
	v_add_f32_e64 v92, v10, v92
	v_add_f32_e64 v93, v11, v93
	v_cvt_pk_bf16_f32 v10, v10, v11
	v_add_f32_e64 v92, v12, v92
	v_add_f32_e64 v93, v13, v93
	v_cvt_pk_bf16_f32 v11, v12, v13
	v_pk_add_f32 v[92:93], v[88:89], v[92:93]
	v_cvt_pk_bf16_f32 v12, v88, v89
	v_pk_add_f32 v[214:215], v[90:91], v[92:93]
	v_cvt_pk_bf16_f32 v13, v90, v91
	v_permlane32_swap_b32_e32 v10, v12
	s_nop 0
	v_permlane32_swap_b32_e32 v11, v13
	v_mfma_f32_32x32x16_bf16 v[112:127], v[80:83], v[172:175], v[112:127]
	v_add_u32_e32 v92, v15, v249
	v_add_u32_e32 v93, v15, v250
	v_add_u32_e32 v94, v15, v251
	v_add_u32_e32 v95, v15, v252
	ds_read_b128 v[96:99], v92
	ds_read_b128 v[100:103], v93
	ds_read_b128 v[104:107], v94
	ds_read_b128 v[80:83], v92 offset:12288
	ds_read_b128 v[84:87], v93 offset:12288
	ds_read_b128 v[88:91], v94 offset:12288
	ds_read_b128 v[222:225], v95 offset:12288
	ds_read_b128 v[92:95], v95
	s_waitcnt lgkmcnt(7)
	v_mfma_f32_32x32x16_bf16 v[112:127], v[96:99], v[176:179], v[112:127]
	s_waitcnt lgkmcnt(6)
	v_mfma_f32_32x32x16_bf16 v[112:127], v[100:103], v[180:183], v[112:127]
	s_waitcnt lgkmcnt(5)
	v_mfma_f32_32x32x16_bf16 v[112:127], v[104:107], v[184:187], v[112:127]
	s_waitcnt lgkmcnt(0)
	v_mfma_f32_32x32x16_bf16 v[96:111], v[92:95], v[188:191], v[112:127]
	v_mfma_f32_32x32x16_bf16 v[128:143], v[80:83], v[176:179], v[128:143]
	v_mfma_f32_32x32x16_bf16 v[128:143], v[84:87], v[180:183], v[128:143]
	v_mfma_f32_32x32x16_bf16 v[128:143], v[88:91], v[184:187], v[128:143]
	v_mfma_f32_32x32x16_bf16 v[80:95], v[222:225], v[188:191], v[128:143]
	v_lshl_add_u32 v15, s7, 14, v237
	ds_read_b64_tr_b16 v[112:113], v15 offset:0
	ds_read_b64_tr_b16 v[114:115], v15 offset:0x800
	ds_read_b64_tr_b16 v[116:117], v15 offset:0x1000
	ds_read_b64_tr_b16 v[118:119], v15 offset:0x1800
	ds_read_b64_tr_b16 v[120:121], v15 offset:0x2000
	ds_read_b64_tr_b16 v[122:123], v15 offset:0x2800
	ds_read_b64_tr_b16 v[124:125], v15 offset:0x3000
	ds_read_b64_tr_b16 v[126:127], v15 offset:0x3800
	ds_read_b64_tr_b16 v[128:129], v15 offset:0x200
	ds_read_b64_tr_b16 v[130:131], v15 offset:0xa00
	ds_read_b64_tr_b16 v[132:133], v15 offset:0x1200
	ds_read_b64_tr_b16 v[134:135], v15 offset:0x1a00
	ds_read_b64_tr_b16 v[136:137], v15 offset:0x2200
	ds_read_b64_tr_b16 v[138:139], v15 offset:0x2a00
	ds_read_b64_tr_b16 v[140:141], v15 offset:0x3200
	ds_read_b64_tr_b16 v[142:143], v15 offset:0x3a00
	s_waitcnt lgkmcnt(8)
	s_nop 0
	v_mfma_f32_32x32x16_bf16 v[64:79], v[2:5], v[112:115], v[64:79]
	v_mfma_f32_32x32x16_bf16 v[64:79], v[6:9], v[116:119], v[64:79]
	v_mfma_f32_32x32x16_bf16 v[64:79], v[192:195], v[120:123], v[64:79]
	v_mfma_f32_32x32x16_bf16 v[64:79], v[10:13], v[124:127], v[64:79]
	ds_read_b64_tr_b16 v[112:113], v15 offset:0x400
	ds_read_b64_tr_b16 v[114:115], v15 offset:0xc00
	ds_read_b64_tr_b16 v[116:117], v15 offset:0x1400
	ds_read_b64_tr_b16 v[118:119], v15 offset:0x1c00
	ds_read_b64_tr_b16 v[120:121], v15 offset:0x2400
	ds_read_b64_tr_b16 v[122:123], v15 offset:0x2c00
	ds_read_b64_tr_b16 v[124:125], v15 offset:0x3400
	ds_read_b64_tr_b16 v[126:127], v15 offset:0x3c00
	s_waitcnt lgkmcnt(8)
	v_mfma_f32_32x32x16_bf16 v[48:63], v[2:5], v[128:131], v[48:63]
	v_mfma_f32_32x32x16_bf16 v[48:63], v[6:9], v[132:135], v[48:63]
	v_mfma_f32_32x32x16_bf16 v[48:63], v[192:195], v[136:139], v[48:63]
	v_mfma_f32_32x32x16_bf16 v[48:63], v[10:13], v[140:143], v[48:63]
	ds_read_b64_tr_b16 v[128:129], v15 offset:0x600
	ds_read_b64_tr_b16 v[130:131], v15 offset:0xe00
	ds_read_b64_tr_b16 v[132:133], v15 offset:0x1600
	ds_read_b64_tr_b16 v[134:135], v15 offset:0x1e00
	ds_read_b64_tr_b16 v[136:137], v15 offset:0x2600
	ds_read_b64_tr_b16 v[138:139], v15 offset:0x2e00
	ds_read_b64_tr_b16 v[140:141], v15 offset:0x3600
	ds_read_b64_tr_b16 v[142:143], v15 offset:0x3e00
	s_waitcnt lgkmcnt(8)
	v_mfma_f32_32x32x16_bf16 v[32:47], v[2:5], v[112:115], v[32:47]
	v_mfma_f32_32x32x16_bf16 v[32:47], v[6:9], v[116:119], v[32:47]
	v_mfma_f32_32x32x16_bf16 v[32:47], v[192:195], v[120:123], v[32:47]
	v_mfma_f32_32x32x16_bf16 v[32:47], v[10:13], v[124:127], v[32:47]
	s_waitcnt lgkmcnt(0)
	v_mfma_f32_32x32x16_bf16 v[16:31], v[2:5], v[128:131], v[16:31]
	s_waitcnt vmcnt(5)
	s_barrier
	s_add_i32 s13, s13, -1
	s_cmp_eq_u32 s13, 0
	v_mfma_f32_32x32x16_bf16 v[16:31], v[6:9], v[132:135], v[16:31]
	v_mfma_f32_32x32x16_bf16 v[16:31], v[192:195], v[136:139], v[16:31]
	v_mfma_f32_32x32x16_bf16 v[16:31], v[10:13], v[140:143], v[16:31]
	s_cbranch_scc1 .LBB0_629
	s_mov_b32 s2, s12
	s_mov_b32 s12, s9
	s_mov_b32 s9, s7
	s_branch .LBB0_624

; template <int MODE, int VARI>
; __device__ __forceinline__ void attn_unit(LAS unsigned char* lds, const int tid, const AttnP& a, float c2, float lam, const float* subln, float outscale, float fox_u, const bool fast) {
;     ...
;       unsigned voff[2], koff[KW / 64], kstp[KW / 64], boff = 0; int vt = t_lo, kt = t_lo;
;       { int tt_ = tid; asm volatile("" : "+v"(tt_)); const int ln_ = tt_ & 63;
; #pragma unroll
;         for (int i_ = 0; i_ < 2; ++i_) { const int ch_ = wid + 8 * i_, b_ = ch_ * 1024 + ln_ * 16, sub_ = b_ >> 9, wi_ = (b_ & 511) >> 1;
;             const int kk_ = (sub_ >> 2) * 8 + (wi_ >> 5), c_ = (sub_ & 3) * 32 + (wi_ & 31), k_ = (kk_ & ~0xC) | ((kk_ & 4) << 1) | ((kk_ & 8) >> 1);
;             voff[i_] = (unsigned)(((t_lo * 64 + k_) * a.vpitch + c_) * 2); }
; #pragma unroll
;         for (int i_ = 0; i_ < KW / 64; ++i_) { const int ch_ = wid + 8 * i_, b_ = ch_ * 1024 + ln_ * 16, krow_ = b_ / (KW * 2), cs_ = (b_ % (KW * 2)) >> 4;
;             const int kcc_ = cs_ ^ (kswz<KW>(krow_) >> 4);
;             if (MODE == 2 && kcc_ >= 8) { koff[i_] = (unsigned)((const char*)a.K1 - (const char*)a.K0) + (unsigned)(((t_lo * 64 + krow_) * a.k1pitch + (kcc_ - 8) * 8) * 2); kstp[i_] = (unsigned)(64 * a.k1pitch * 2); }
;             else { koff[i_] = (unsigned)(((t_lo * 64 + krow_) * a.k0pitch + kcc_ * 8) * 2); kstp[i_] = (unsigned)(64 * a.k0pitch * 2); } }
;         if (MODE == 1) boff = (unsigned)((t_lo * 64 + ln_) * 32); }
.LBB0_821:
	s_mov_b32 s12, s14
	s_lshl_b32 s14, s2, 14
	s_mov_b32 s63, s70
	s_mov_b32 s70, s2
	s_add_i32 s2, s9, s14
	s_add_i32 m0, s2, 0xc000
	v_add_u32_e32 v0, 0x98000, v163
	global_load_lds_dwordx4 v165, s[60:61]
	s_add_i32 m0, s2, 0xe000
	s_cmp_lt_u32 s83, s57
	s_cselect_b64 s[18:19], -1, 0
	s_and_b64 s[34:35], s[18:19], exec
	s_cselect_b32 s2, 0x98000, 0
	s_cmp_lg_u64 s[18:19], 0
	global_load_lds_dwordx4 v164, s[60:61]
	v_add_u32_e32 v164, s2, v164
	v_add_u32_e32 v165, s2, v165
	s_addc_u32 s83, s83, 0
	s_lshl_b32 s2, s63, 14
	s_add_i32 s2, s9, s2
	s_mov_b32 m0, s2
	v_add_u32_e32 v98, 0x98000, v162
	global_load_lds_dwordx4 v163, s[76:77]
	s_add_i32 m0, s2, 0x2000
	s_cmp_lt_u32 s62, s57
	global_load_lds_dwordx4 v162, s[76:77]
	s_cselect_b64 vcc, -1, 0
	s_cmp_lg_u64 vcc, 0
	v_cndmask_b32_e32 v162, v162, v98, vcc
	v_cndmask_b32_e32 v163, v163, v0, vcc
	s_addc_u32 s62, s62, 0
	v_lshl_add_u32 v0, s12, 14, v160
	v_add_u32_e32 v102, v0, v166
	v_exp_f32_e32 v150, v82
	v_exp_f32_e32 v151, v83
	v_exp_f32_e32 v152, v84
	v_exp_f32_e32 v153, v85
	ds_read_b128 v[98:101], v102
	ds_read_b128 v[114:117], v102 offset:8192
	v_exp_f32_e32 v170, v86
	v_exp_f32_e32 v171, v87
	v_exp_f32_e32 v172, v88
	v_exp_f32_e32 v173, v89
	v_cvt_pk_bf16_f32 v146, v150, v151
	v_cvt_pk_bf16_f32 v147, v152, v153
	v_cvt_pk_bf16_f32 v148, v170, v171
	v_cvt_pk_bf16_f32 v149, v172, v173
	s_waitcnt lgkmcnt(0)
	v_mfma_f32_32x32x16_bf16 v[98:113], v[98:101], v[130:133], 0
	v_permlane32_swap_b32_e32 v146, v148
	v_permlane32_swap_b32_e32 v147, v149
	v_mfma_f32_32x32x16_bf16 v[114:129], v[114:117], v[130:133], 0
	v_add_u32_e32 v86, v0, v167
	v_mov_b32_e32 v174, v92
	v_mov_b32_e32 v175, v93
	ds_read_b128 v[82:85], v86
	ds_read_b128 v[86:89], v86 offset:8192
	v_exp_f32_e32 v90, v90
	v_exp_f32_e32 v91, v91
	v_pk_add_f32 v[92:93], v[156:157], v[150:151]
	v_exp_f32_e32 v156, v174
	v_exp_f32_e32 v157, v175
	v_exp_f32_e32 v174, v94
	v_exp_f32_e32 v175, v95
	v_exp_f32_e32 v176, v96
	v_exp_f32_e32 v177, v97
	v_pk_add_f32 v[92:93], v[152:153], v[92:93]
	v_cvt_pk_bf16_f32 v150, v90, v91
	v_pk_add_f32 v[92:93], v[170:171], v[92:93]
	v_cvt_pk_bf16_f32 v151, v156, v157
	v_pk_add_f32 v[92:93], v[172:173], v[92:93]
	v_cvt_pk_bf16_f32 v152, v174, v175
	v_pk_add_f32 v[92:93], v[90:91], v[92:93]
	v_cvt_pk_bf16_f32 v153, v176, v177
	s_waitcnt lgkmcnt(0)
	v_mfma_f32_32x32x16_bf16 v[114:129], v[86:89], v[134:137], v[114:129]
	v_permlane32_swap_b32_e32 v150, v152
	v_permlane32_swap_b32_e32 v151, v153
	v_mfma_f32_32x32x16_bf16 v[98:113], v[82:85], v[134:137], v[98:113]
	v_add_u32_e32 v86, v0, v168
	v_exp_f32_e32 v178, v66
	v_exp_f32_e32 v179, v67
	v_exp_f32_e32 v180, v68
	v_exp_f32_e32 v181, v69
	ds_read_b128 v[82:85], v86
	ds_read_b128 v[86:89], v86 offset:8192
	v_exp_f32_e32 v182, v70
	v_exp_f32_e32 v183, v71
	v_exp_f32_e32 v184, v72
	v_exp_f32_e32 v185, v73
	v_cvt_pk_bf16_f32 v170, v178, v179
	v_cvt_pk_bf16_f32 v171, v180, v181
	v_cvt_pk_bf16_f32 v172, v182, v183
	v_cvt_pk_bf16_f32 v173, v184, v185
	s_waitcnt lgkmcnt(0)
	v_mfma_f32_32x32x16_bf16 v[98:113], v[82:85], v[138:141], v[98:113]
	v_permlane32_swap_b32_e32 v170, v172
	v_permlane32_swap_b32_e32 v171, v173
	v_mfma_f32_32x32x16_bf16 v[114:129], v[86:89], v[138:141], v[114:129]
	v_add_u32_e32 v0, v0, v169
	v_add_f32_e64 v156, v156, v92
	v_add_f32_e64 v157, v157, v93
	ds_read_b128 v[232:235], v0
	ds_read_b128 v[236:239], v0 offset:8192
	v_mov_b32_e32 v193, v81
	v_pk_add_f32 v[248:249], v[174:175], v[156:157]
	v_exp_f32_e32 v240, v74
	v_pk_add_f32 v[248:249], v[176:177], v[248:249]
	v_exp_f32_e32 v241, v75
	v_pk_add_f32 v[248:249], v[178:179], v[248:249]
	s_waitcnt lgkmcnt(0)
; #define SBAR() __builtin_amdgcn_sched_barrier(0)
; #define VSET(S, d0) do { constexpr int b_ = (d0) * 512; TRRD(S##l0, b_); TRRD(S##h0, b_ + 2048); TRRD(S##l1, b_ + 4096); TRRD(S##h1, b_ + 6144); \
;         TRRD(S##l2, b_ + 8192); TRRD(S##h2, b_ + 10240); TRRD(S##l3, b_ + 12288); TRRD(S##h3, b_ + 14336); } while (0)
; #define LWAIT(n) do { asm volatile("s_waitcnt lgkmcnt(" #n ")" ::: "memory"); SBAR(); } while (0)
; __device__ __forceinline__ void pv_tile(f32x16* o, unsigned vb, bf16x8 pa0, bf16x8 pa1, bf16x8 pa2, bf16x8 pa3) {
;     ...
;     s16x4 Al0, Al1, Al2, Al3, Ah0, Ah1, Ah2, Ah3, Bl0, Bl1, Bl2, Bl3, Bh0, Bh1, Bh2, Bh3;
;     VSET(A, 0);
;     VSET(B, 1); LWAIT(8); VMMA(A, 0); SBAR();
;     VSET(A, 2); LWAIT(8); VMMA(B, 1); SBAR();
;     VSET(B, 3); LWAIT(8); VMMA(A, 2); SBAR();
;     LWAIT(0); VMMA(B, 3);
	v_mfma_f32_32x32x16_bf16 v[82:97], v[232:235], v[142:145], v[98:113]
	v_exp_f32_e32 v242, v76
	v_exp_f32_e32 v243, v77
	v_pk_add_f32 v[250:251], v[180:181], v[248:249]
	v_exp_f32_e32 v244, v78
	v_exp_f32_e32 v245, v79
	v_pk_add_f32 v[248:249], v[182:183], v[250:251]
	v_exp_f32_e32 v246, v80
	v_mfma_f32_32x32x16_bf16 v[66:81], v[236:239], v[142:145], v[114:129]
	v_exp_f32_e32 v247, v193
	v_pk_add_f32 v[248:249], v[184:185], v[248:249]
	v_cvt_pk_bf16_f32 v98, v240, v241
	v_pk_add_f32 v[250:251], v[240:241], v[248:249]
	v_cvt_pk_bf16_f32 v99, v242, v243
	v_pk_add_f32 v[250:251], v[242:243], v[250:251]
	v_cvt_pk_bf16_f32 v100, v244, v245
	v_pk_add_f32 v[250:251], v[244:245], v[250:251]
	v_cvt_pk_bf16_f32 v101, v246, v247
	v_pk_add_f32 v[156:157], v[246:247], v[250:251]
	v_permlane32_swap_b32_e32 v98, v100
	v_permlane32_swap_b32_e32 v99, v101
	v_add_u32_e32 v0, s14, v161
	ds_read_b64_tr_b16 v[102:103], v0 offset:0
	ds_read_b64_tr_b16 v[104:105], v0 offset:0x800
	ds_read_b64_tr_b16 v[106:107], v0 offset:0x1000
	ds_read_b64_tr_b16 v[108:109], v0 offset:0x1800
	ds_read_b64_tr_b16 v[110:111], v0 offset:0x2000
	ds_read_b64_tr_b16 v[112:113], v0 offset:0x2800
	ds_read_b64_tr_b16 v[114:115], v0 offset:0x3000
	ds_read_b64_tr_b16 v[116:117], v0 offset:0x3800
	ds_read_b64_tr_b16 v[118:119], v0 offset:0x200
	ds_read_b64_tr_b16 v[120:121], v0 offset:0xa00
	ds_read_b64_tr_b16 v[122:123], v0 offset:0x1200
	ds_read_b64_tr_b16 v[124:125], v0 offset:0x1a00
	ds_read_b64_tr_b16 v[126:127], v0 offset:0x2200
	ds_read_b64_tr_b16 v[128:129], v0 offset:0x2a00
	ds_read_b64_tr_b16 v[174:175], v0 offset:0x3200
	ds_read_b64_tr_b16 v[176:177], v0 offset:0x3a00
	s_waitcnt lgkmcnt(8)
	s_nop 0
	v_mfma_f32_32x32x16_bf16 v[50:65], v[146:149], v[102:105], v[50:65]
	v_mfma_f32_32x32x16_bf16 v[50:65], v[150:153], v[106:109], v[50:65]
	v_mfma_f32_32x32x16_bf16 v[50:65], v[170:173], v[110:113], v[50:65]
	v_mfma_f32_32x32x16_bf16 v[50:65], v[98:101], v[114:117], v[50:65]
	ds_read_b64_tr_b16 v[102:103], v0 offset:0x400
	ds_read_b64_tr_b16 v[104:105], v0 offset:0xc00
	ds_read_b64_tr_b16 v[106:107], v0 offset:0x1400
	ds_read_b64_tr_b16 v[108:109], v0 offset:0x1c00
	ds_read_b64_tr_b16 v[110:111], v0 offset:0x2400
	ds_read_b64_tr_b16 v[112:113], v0 offset:0x2c00
	ds_read_b64_tr_b16 v[114:115], v0 offset:0x3400
	ds_read_b64_tr_b16 v[116:117], v0 offset:0x3c00
	s_waitcnt lgkmcnt(8)
	v_mfma_f32_32x32x16_bf16 v[34:49], v[146:149], v[118:121], v[34:49]
	v_mfma_f32_32x32x16_bf16 v[34:49], v[150:153], v[122:125], v[34:49]
	v_mfma_f32_32x32x16_bf16 v[34:49], v[170:173], v[126:129], v[34:49]
	v_mfma_f32_32x32x16_bf16 v[34:49], v[98:101], v[174:177], v[34:49]
	ds_read_b64_tr_b16 v[118:119], v0 offset:0x600
	ds_read_b64_tr_b16 v[120:121], v0 offset:0xe00
	ds_read_b64_tr_b16 v[122:123], v0 offset:0x1600
	ds_read_b64_tr_b16 v[124:125], v0 offset:0x1e00
	ds_read_b64_tr_b16 v[126:127], v0 offset:0x2600
	ds_read_b64_tr_b16 v[128:129], v0 offset:0x2e00
	ds_read_b64_tr_b16 v[174:175], v0 offset:0x3600
	ds_read_b64_tr_b16 v[176:177], v0 offset:0x3e00
	s_waitcnt lgkmcnt(8)
	v_mfma_f32_32x32x16_bf16 v[18:33], v[146:149], v[102:105], v[18:33]
	v_mfma_f32_32x32x16_bf16 v[18:33], v[150:153], v[106:109], v[18:33]
	v_mfma_f32_32x32x16_bf16 v[18:33], v[170:173], v[110:113], v[18:33]
	v_mfma_f32_32x32x16_bf16 v[18:33], v[98:101], v[114:117], v[18:33]
	s_waitcnt lgkmcnt(0)
	v_mfma_f32_32x32x16_bf16 v[2:17], v[146:149], v[118:121], v[2:17]
	s_waitcnt vmcnt(4)
	s_barrier
	s_add_i32 s13, s13, -1
	s_cmp_lg_u32 s13, 0
	s_mov_b32 s2, s12
	s_mov_b32 s14, s63
	v_mfma_f32_32x32x16_bf16 v[2:17], v[150:153], v[122:125], v[2:17]
	v_mfma_f32_32x32x16_bf16 v[2:17], v[170:173], v[126:129], v[2:17]
	v_mfma_f32_32x32x16_bf16 v[2:17], v[98:101], v[174:177], v[2:17]
	s_cbranch_scc1 .LBB0_821
	s_branch .LBB0_823

; template <int MODE, int VARI>
; __device__ __forceinline__ void attn_unit(LAS unsigned char* lds, const int tid, const AttnP& a, float c2, float lam, const float* subln, float outscale, float fox_u, const bool fast) {
;     ...
;       unsigned voff[2], koff[KW / 64], kstp[KW / 64], boff = 0; int vt = t_lo, kt = t_lo;
;       { int tt_ = tid; asm volatile("" : "+v"(tt_)); const int ln_ = tt_ & 63;
; #pragma unroll
;         for (int i_ = 0; i_ < 2; ++i_) { const int ch_ = wid + 8 * i_, b_ = ch_ * 1024 + ln_ * 16, sub_ = b_ >> 9, wi_ = (b_ & 511) >> 1;
;             const int kk_ = (sub_ >> 2) * 8 + (wi_ >> 5), c_ = (sub_ & 3) * 32 + (wi_ & 31), k_ = (kk_ & ~0xC) | ((kk_ & 4) << 1) | ((kk_ & 8) >> 1);
;             voff[i_] = (unsigned)(((t_lo * 64 + k_) * a.vpitch + c_) * 2); }
; #pragma unroll
;         for (int i_ = 0; i_ < KW / 64; ++i_) { const int ch_ = wid + 8 * i_, b_ = ch_ * 1024 + ln_ * 16, krow_ = b_ / (KW * 2), cs_ = (b_ % (KW * 2)) >> 4;
;             const int kcc_ = cs_ ^ (kswz<KW>(krow_) >> 4);
;             if (MODE == 2 && kcc_ >= 8) { koff[i_] = (unsigned)((const char*)a.K1 - (const char*)a.K0) + (unsigned)(((t_lo * 64 + krow_) * a.k1pitch + (kcc_ - 8) * 8) * 2); kstp[i_] = (unsigned)(64 * a.k1pitch * 2); }
;             else { koff[i_] = (unsigned)(((t_lo * 64 + krow_) * a.k0pitch + kcc_ * 8) * 2); kstp[i_] = (unsigned)(64 * a.k0pitch * 2); } }
;         if (MODE == 1) boff = (unsigned)((t_lo * 64 + ln_) * 32); }
.LBB0_969:
	s_cmp_lt_i32 s83, s7
	s_cselect_b64 s[18:19], -1, 0
	s_and_b64 s[34:35], s[18:19], exec
	s_cselect_b32 s2, 0x98000, 0
	s_cmp_lg_u64 s[18:19], 0
	v_add_u32_e32 v186, s2, v186
	v_add_u32_e32 v187, s2, v187
	s_addc_u32 s83, s83, 0
	v_lshl_add_u32 v181, s57, 14, v15
	v_lshl_add_u32 v213, s13, 8, v212
	v_add_u32_e32 v10, v181, v188
	ds_read_b128 v[2:5], v213
	ds_read_b128 v[6:9], v10
	ds_read_b128 v[10:13], v10 offset:8192
	s_waitcnt lgkmcnt(0)
	v_mfma_f32_32x32x16_bf16 v[112:127], v[6:9], v[144:147], 0
	v_sub_f32_e32 v2, v180, v2
	v_sub_f32_e32 v3, v180, v3
	v_sub_f32_e32 v4, v180, v4
	v_sub_f32_e32 v5, v180, v5
	v_fmac_f32_e32 v2, 0x3e0293ee, v96
	v_fmac_f32_e32 v3, 0x3e0293ee, v97
	v_fmac_f32_e32 v4, 0x3e0293ee, v98
	v_fmac_f32_e32 v5, 0x3e0293ee, v99
	v_exp_f32_e32 v214, v2
	v_exp_f32_e32 v215, v3
	v_exp_f32_e32 v222, v4
	v_exp_f32_e32 v223, v5
	v_mfma_f32_32x32x16_bf16 v[128:143], v[10:13], v[144:147], 0
	ds_read_b128 v[2:5], v213 offset:32
	v_add_u32_e32 v10, v181, v189
	ds_read_b128 v[6:9], v10
	ds_read_b128 v[10:13], v10 offset:8192
	s_waitcnt lgkmcnt(0)
	v_mfma_f32_32x32x16_bf16 v[128:143], v[10:13], v[148:151], v[128:143]
	v_sub_f32_e32 v2, v180, v2
	v_sub_f32_e32 v3, v180, v3
	v_sub_f32_e32 v4, v180, v4
	v_sub_f32_e32 v5, v180, v5
	v_fmac_f32_e32 v2, 0x3e0293ee, v100
	v_fmac_f32_e32 v3, 0x3e0293ee, v101
	v_fmac_f32_e32 v4, 0x3e0293ee, v102
	v_fmac_f32_e32 v5, 0x3e0293ee, v103
	v_exp_f32_e32 v100, v2
	v_exp_f32_e32 v101, v3
	v_exp_f32_e32 v102, v4
	v_exp_f32_e32 v103, v5
	v_cvt_pk_bf16_f32 v2, v214, v215
	v_cvt_pk_bf16_f32 v3, v222, v223
	v_cvt_pk_bf16_f32 v4, v100, v101
	v_cvt_pk_bf16_f32 v5, v102, v103
	s_nop 0
	v_permlane32_swap_b32_e32 v2, v4
	v_permlane32_swap_b32_e32 v3, v5
	v_mfma_f32_32x32x16_bf16 v[112:127], v[6:9], v[148:151], v[112:127]
	ds_read_b128 v[6:9], v213 offset:64
	v_add_u32_e32 v96, v181, v190
	ds_read_b128 v[10:13], v96
	ds_read_b128 v[96:99], v96 offset:8192
	s_waitcnt lgkmcnt(0)
	v_mfma_f32_32x32x16_bf16 v[112:127], v[10:13], v[152:155], v[112:127]
	v_sub_f32_e32 v6, v180, v6
	v_sub_f32_e32 v7, v180, v7
	v_fmac_f32_e32 v6, 0x3e0293ee, v104
	v_fmac_f32_e32 v7, 0x3e0293ee, v105
	v_sub_f32_e32 v8, v180, v8
	v_sub_f32_e32 v9, v180, v9
	v_fmac_f32_e32 v8, 0x3e0293ee, v106
	v_fmac_f32_e32 v9, 0x3e0293ee, v107
	v_exp_f32_e32 v104, v6
	v_exp_f32_e32 v105, v7
	v_pk_add_f32 v[6:7], v[182:183], v[214:215]
	v_exp_f32_e32 v182, v8
	v_pk_add_f32 v[6:7], v[222:223], v[6:7]
	v_exp_f32_e32 v183, v9
	v_pk_add_f32 v[6:7], v[6:7], v[100:101]
	v_mfma_f32_32x32x16_bf16 v[128:143], v[96:99], v[152:155], v[128:143]
	v_add_f32_e64 v6, v102, v6
	v_add_f32_e64 v7, v103, v7
	v_add_f32_e64 v106, v6, v104
	v_add_f32_e64 v107, v7, v105
	ds_read_b128 v[6:9], v213 offset:96
	v_add_u32_e32 v96, v181, v191
	ds_read_b128 v[10:13], v96
	ds_read_b128 v[96:99], v96 offset:8192
	s_waitcnt lgkmcnt(0)
	v_mfma_f32_32x32x16_bf16 v[128:143], v[96:99], v[156:159], v[128:143]
	v_sub_f32_e32 v6, v180, v6
	v_sub_f32_e32 v7, v180, v7
	v_sub_f32_e32 v8, v180, v8
	v_sub_f32_e32 v9, v180, v9
	v_fmac_f32_e32 v6, 0x3e0293ee, v108
	v_fmac_f32_e32 v7, 0x3e0293ee, v109
	v_fmac_f32_e32 v8, 0x3e0293ee, v110
	v_fmac_f32_e32 v9, 0x3e0293ee, v111
	v_exp_f32_e32 v108, v6
	v_exp_f32_e32 v109, v7
	v_exp_f32_e32 v110, v8
	v_exp_f32_e32 v111, v9
	v_cvt_pk_bf16_f32 v6, v104, v105
	v_cvt_pk_bf16_f32 v7, v182, v183
	v_cvt_pk_bf16_f32 v8, v108, v109
	v_cvt_pk_bf16_f32 v9, v110, v111
	s_nop 0
	v_permlane32_swap_b32_e32 v6, v8
	v_permlane32_swap_b32_e32 v7, v9
	v_mfma_f32_32x32x16_bf16 v[112:127], v[10:13], v[156:159], v[112:127]
	v_add_u32_e32 v100, v181, v192
	ds_read_b128 v[10:13], v213 offset:128
	ds_read_b128 v[96:99], v100
	ds_read_b128 v[100:103], v100 offset:8192
	s_waitcnt lgkmcnt(0)
	v_mfma_f32_32x32x16_bf16 v[112:127], v[96:99], v[160:163], v[112:127]
	v_sub_f32_e32 v10, v180, v10
	v_sub_f32_e32 v11, v180, v11
	v_fmac_f32_e32 v10, 0x3e0293ee, v80
	v_fmac_f32_e32 v11, 0x3e0293ee, v81
	v_exp_f32_e32 v104, v10
	v_exp_f32_e32 v105, v11
	v_sub_f32_e32 v12, v180, v12
	v_sub_f32_e32 v13, v180, v13
	v_fmac_f32_e32 v12, 0x3e0293ee, v82
	v_fmac_f32_e32 v13, 0x3e0293ee, v83
	v_exp_f32_e32 v214, v12
	v_exp_f32_e32 v215, v13
	v_mfma_f32_32x32x16_bf16 v[128:143], v[100:103], v[160:163], v[128:143]
	ds_read_b128 v[10:13], v213 offset:160
	v_add_u32_e32 v96, v181, v193
	ds_read_b128 v[80:83], v96
	ds_read_b128 v[96:99], v96 offset:8192
	s_waitcnt lgkmcnt(0)
	v_mfma_f32_32x32x16_bf16 v[128:143], v[96:99], v[164:167], v[128:143]
	v_sub_f32_e32 v10, v180, v10
	v_sub_f32_e32 v11, v180, v11
	v_sub_f32_e32 v12, v180, v12
	v_sub_f32_e32 v13, v180, v13
	v_fmac_f32_e32 v10, 0x3e0293ee, v84
	v_fmac_f32_e32 v11, 0x3e0293ee, v85
	v_fmac_f32_e32 v12, 0x3e0293ee, v86
	v_fmac_f32_e32 v13, 0x3e0293ee, v87
	v_exp_f32_e32 v100, v10
	v_exp_f32_e32 v101, v11
	v_exp_f32_e32 v102, v12
	v_exp_f32_e32 v103, v13
	v_cvt_pk_bf16_f32 v10, v104, v105
	v_cvt_pk_bf16_f32 v11, v214, v215
	v_cvt_pk_bf16_f32 v12, v100, v101
	v_cvt_pk_bf16_f32 v13, v102, v103
	s_nop 0
	v_permlane32_swap_b32_e32 v10, v12
	v_permlane32_swap_b32_e32 v11, v13
	v_mfma_f32_32x32x16_bf16 v[112:127], v[80:83], v[164:167], v[112:127]
	v_add_u32_e32 v96, v181, v194
	ds_read_b128 v[80:83], v213 offset:192
	ds_read_b128 v[84:87], v96
	ds_read_b128 v[96:99], v96 offset:8192
	s_waitcnt lgkmcnt(0)
; #define SBAR() __builtin_amdgcn_sched_barrier(0)
; #define VSET(S, d0) do { constexpr int b_ = (d0) * 512; TRRD(S##l0, b_); TRRD(S##h0, b_ + 2048); TRRD(S##l1, b_ + 4096); TRRD(S##h1, b_ + 6144); \
;         TRRD(S##l2, b_ + 8192); TRRD(S##h2, b_ + 10240); TRRD(S##l3, b_ + 12288); TRRD(S##h3, b_ + 14336); } while (0)
; #define LWAIT(n) do { asm volatile("s_waitcnt lgkmcnt(" #n ")" ::: "memory"); SBAR(); } while (0)
; __device__ __forceinline__ void pv_tile(f32x16* o, unsigned vb, bf16x8 pa0, bf16x8 pa1, bf16x8 pa2, bf16x8 pa3) {
;     ...
;     s16x4 Al0, Al1, Al2, Al3, Ah0, Ah1, Ah2, Ah3, Bl0, Bl1, Bl2, Bl3, Bh0, Bh1, Bh2, Bh3;
;     VSET(A, 0);
;     VSET(B, 1); LWAIT(8); VMMA(A, 0); SBAR();
;     VSET(A, 2); LWAIT(8); VMMA(B, 1); SBAR();
;     VSET(B, 3); LWAIT(8); VMMA(A, 2); SBAR();
;     LWAIT(0); VMMA(B, 3);
	v_mfma_f32_32x32x16_bf16 v[112:127], v[84:87], v[168:171], v[112:127]
	v_sub_f32_e32 v80, v180, v80
	v_sub_f32_e32 v81, v180, v81
	v_sub_f32_e32 v82, v180, v82
	v_sub_f32_e32 v83, v180, v83
	v_fmac_f32_e32 v80, 0x3e0293ee, v88
	v_fmac_f32_e32 v81, 0x3e0293ee, v89
	v_fmac_f32_e32 v82, 0x3e0293ee, v90
	v_fmac_f32_e32 v83, 0x3e0293ee, v91
	v_exp_f32_e32 v88, v80
	v_exp_f32_e32 v89, v81
	v_exp_f32_e32 v90, v82
	v_exp_f32_e32 v91, v83
	v_mfma_f32_32x32x16_bf16 v[128:143], v[96:99], v[168:171], v[128:143]
	ds_read_b128 v[80:83], v213 offset:224
	v_add_u32_e32 v96, v181, v195
	ds_read_b128 v[84:87], v96
	ds_read_b128 v[232:235], v96 offset:8192
	v_cvt_pk_bf16_f32 v236, v88, v89
	v_cvt_pk_bf16_f32 v237, v90, v91
	s_waitcnt lgkmcnt(0)
	v_sub_f32_e32 v80, v180, v80
	v_sub_f32_e32 v81, v180, v81
	v_fmac_f32_e32 v80, 0x3e0293ee, v92
	v_fmac_f32_e32 v81, 0x3e0293ee, v93
	v_pk_add_f32 v[92:93], v[182:183], v[106:107]
	v_sub_f32_e32 v82, v180, v82
	v_pk_add_f32 v[92:93], v[92:93], v[108:109]
	v_sub_f32_e32 v83, v180, v83
	v_pk_add_f32 v[92:93], v[110:111], v[92:93]
	v_fmac_f32_e32 v82, 0x3e0293ee, v94
	v_pk_add_f32 v[92:93], v[92:93], v[104:105]
	v_fmac_f32_e32 v83, 0x3e0293ee, v95
	v_pk_add_f32 v[92:93], v[214:215], v[92:93]
	v_exp_f32_e32 v80, v80
	v_exp_f32_e32 v81, v81
	v_pk_add_f32 v[92:93], v[92:93], v[100:101]
	v_exp_f32_e32 v82, v82
	v_exp_f32_e32 v83, v83
	v_pk_add_f32 v[92:93], v[102:103], v[92:93]
	v_pk_add_f32 v[92:93], v[92:93], v[88:89]
	v_pk_add_f32 v[92:93], v[90:91], v[92:93]
	v_pk_add_f32 v[92:93], v[92:93], v[80:81]
	v_pk_add_f32 v[182:183], v[82:83], v[92:93]
	v_cvt_pk_bf16_f32 v238, v80, v81
	v_mfma_f32_32x32x16_bf16 v[96:111], v[84:87], v[172:175], v[112:127]
	v_cvt_pk_bf16_f32 v239, v82, v83
	v_permlane32_swap_b32_e32 v236, v238
	v_mfma_f32_32x32x16_bf16 v[80:95], v[232:235], v[172:175], v[128:143]
	v_permlane32_swap_b32_e32 v237, v239
	v_add_u32_e32 v181, s15, v179
	ds_read_b64_tr_b16 v[112:113], v181 offset:0
	ds_read_b64_tr_b16 v[114:115], v181 offset:0x800
	ds_read_b64_tr_b16 v[116:117], v181 offset:0x1000
	ds_read_b64_tr_b16 v[118:119], v181 offset:0x1800
	ds_read_b64_tr_b16 v[120:121], v181 offset:0x2000
	ds_read_b64_tr_b16 v[122:123], v181 offset:0x2800
	ds_read_b64_tr_b16 v[124:125], v181 offset:0x3000
	ds_read_b64_tr_b16 v[126:127], v181 offset:0x3800
	ds_read_b64_tr_b16 v[128:129], v181 offset:0x200
	ds_read_b64_tr_b16 v[130:131], v181 offset:0xa00
	ds_read_b64_tr_b16 v[132:133], v181 offset:0x1200
	ds_read_b64_tr_b16 v[134:135], v181 offset:0x1a00
	ds_read_b64_tr_b16 v[136:137], v181 offset:0x2200
	ds_read_b64_tr_b16 v[138:139], v181 offset:0x2a00
	ds_read_b64_tr_b16 v[140:141], v181 offset:0x3200
	ds_read_b64_tr_b16 v[142:143], v181 offset:0x3a00
	s_waitcnt lgkmcnt(8)
	s_nop 0
	v_mfma_f32_32x32x16_bf16 v[64:79], v[2:5], v[112:115], v[64:79]
	v_mfma_f32_32x32x16_bf16 v[64:79], v[6:9], v[116:119], v[64:79]
	v_mfma_f32_32x32x16_bf16 v[64:79], v[10:13], v[120:123], v[64:79]
	v_mfma_f32_32x32x16_bf16 v[64:79], v[236:239], v[124:127], v[64:79]
	ds_read_b64_tr_b16 v[112:113], v181 offset:0x400
	ds_read_b64_tr_b16 v[114:115], v181 offset:0xc00
	ds_read_b64_tr_b16 v[116:117], v181 offset:0x1400
	ds_read_b64_tr_b16 v[118:119], v181 offset:0x1c00
	ds_read_b64_tr_b16 v[120:121], v181 offset:0x2400
	ds_read_b64_tr_b16 v[122:123], v181 offset:0x2c00
	ds_read_b64_tr_b16 v[124:125], v181 offset:0x3400
	ds_read_b64_tr_b16 v[126:127], v181 offset:0x3c00
	s_waitcnt lgkmcnt(8)
	v_mfma_f32_32x32x16_bf16 v[48:63], v[2:5], v[128:131], v[48:63]
	v_mfma_f32_32x32x16_bf16 v[48:63], v[6:9], v[132:135], v[48:63]
	v_mfma_f32_32x32x16_bf16 v[48:63], v[10:13], v[136:139], v[48:63]
	v_mfma_f32_32x32x16_bf16 v[48:63], v[236:239], v[140:143], v[48:63]
	ds_read_b64_tr_b16 v[128:129], v181 offset:0x600
	ds_read_b64_tr_b16 v[130:131], v181 offset:0xe00
	ds_read_b64_tr_b16 v[132:133], v181 offset:0x1600
	ds_read_b64_tr_b16 v[134:135], v181 offset:0x1e00
	ds_read_b64_tr_b16 v[136:137], v181 offset:0x2600
	ds_read_b64_tr_b16 v[138:139], v181 offset:0x2e00
	ds_read_b64_tr_b16 v[140:141], v181 offset:0x3600
	ds_read_b64_tr_b16 v[142:143], v181 offset:0x3e00
	s_waitcnt lgkmcnt(8)
	v_mfma_f32_32x32x16_bf16 v[32:47], v[2:5], v[112:115], v[32:47]
	v_mfma_f32_32x32x16_bf16 v[32:47], v[6:9], v[116:119], v[32:47]
	v_mfma_f32_32x32x16_bf16 v[32:47], v[10:13], v[120:123], v[32:47]
	v_mfma_f32_32x32x16_bf16 v[32:47], v[236:239], v[124:127], v[32:47]
	s_waitcnt lgkmcnt(0)
	v_mfma_f32_32x32x16_bf16 v[16:31], v[2:5], v[128:131], v[16:31]
	s_waitcnt vmcnt(5)
	s_barrier
	s_add_i32 s6, s6, 1
	s_cmp_ge_i32 s6, s8
	s_mov_b32 s15, s57
	s_mov_b32 s57, s63
	v_mfma_f32_32x32x16_bf16 v[16:31], v[6:9], v[132:135], v[16:31]
	s_mov_b32 s63, s13
	v_mfma_f32_32x32x16_bf16 v[16:31], v[10:13], v[136:139], v[16:31]
	v_mfma_f32_32x32x16_bf16 v[16:31], v[236:239], v[140:143], v[16:31]
	s_cbranch_scc1 .LBB0_973
